# mixer-A phase: odd blocks run their attention items before their mLSTM-A items (even blocks unchanged) so HBM-bound and compute-bound sub-phases overlap chip-wide
# baseline (speedup 1.0000x reference)
; DI int otid() { int t = __builtin_amdgcn_workitem_id_x(); asm volatile("" : "+v"(t)); return t; }
; DI void mlstmA_item(const Params& p, char* lds, int item) {
;   char* ws = p.ws;
;   const int bh = item >> 7, c = item & 127, b = bh >> 2, hd = bh & 3;
;   const int tid = otid(), lane = tid & 63, wave = tid >> 6, hh = lane >> 5, l31 = lane & 31;
;   u16* KTs = (u16*)lds;
;   u16* VTs = KTs + 128 * 72;
;   float* win = (float*)(VTs + 128 * 72);
;   const u16* PM = (const u16*)(ws + OFF_PM); const u16* VTm = (const u16*)(ws + OFF_VTM);
;   const float* G = (const float*)(ws + OFF_G);
;   u16* KVS = (u16*)(ws + OFF_KVS) + (size_t)item * 16384; float* KSUM = (float*)(ws + OFF_KSUM) + (size_t)item * 128; float* CSC = (float*)(ws + OFF_CSC) + (size_t)item * 4;
; DI void phase_mixA(const Params& p, char* lds) {
;   for (int it = blockIdx.x; it < 4096; it += gridDim.x) mlstmA_item(p, lds, it);
;   if ((gridDim.x & 7) == 0 && gridDim.x <= 256) {
;     const int x = blockIdx.x & 7, slot = blockIdx.x >> 3, nx = gridDim.x >> 3;
;     for (int j = slot; j < 256; j += nx) attn_item(p, lds, x * 256 + j);
;   } else {
;     for (int it = blockIdx.x; it < 2048; it += gridDim.x) attn_item(p, lds, it);
;   }
.LBB0_321:
	s_or_b64 exec, exec, s[0:1]
	s_cmpk_gt_i32 s94, 0xfff
	s_waitcnt lgkmcnt(0)
	s_barrier
	s_and_b32 s98, s94, 1
	s_cmp_eq_u32 s98, 1
	s_cbranch_scc1 .LBB0_342
.Lmixa_astart:
	s_add_u32 s4, s68, 0x16800000
	s_addc_u32 s5, s69, 0
	s_add_u32 s6, s68, 0x22800000
	s_addc_u32 s7, s69, 0
	s_add_u32 s2, s68, 0x32800000
	s_addc_u32 s16, s69, 0
	s_add_u32 s17, s68, 0x3a800000
	s_addc_u32 s20, s69, 0
	v_mbcnt_hi_u32_b32 v34, -1, v203
	s_add_u32 s21, s68, 0x3aa00000
	v_and_b32_e32 v35, 64, v34
	v_bfrev_b32_e32 v0, 0.5
	s_addc_u32 s22, s69, 0
	s_mov_b32 s9, 0
	s_mov_b32 s23, 0xbfb8aa3b
	v_mov_b32_e32 v32, 0x3ecc95a3
	v_mov_b32_e32 v17, 0
	s_movk_i32 s26, 0x90
	v_mov_b32_e32 v33, 0x7f800000
	v_add_u32_e32 v36, -1, v34
	v_add_u32_e32 v37, -2, v34
	v_add_u32_e32 v38, -4, v34
	v_add_u32_e32 v39, -8, v34
	v_add_u32_e32 v40, -16, v34
	v_subrev_u32_e32 v41, 32, v34
	v_add_u32_e32 v42, 64, v35
	v_xor_b32_e32 v43, 32, v34
	v_xor_b32_e32 v44, 16, v34
	v_xor_b32_e32 v45, 8, v34
	v_xor_b32_e32 v46, 4, v34
	v_xor_b32_e32 v47, 2, v34
	v_xor_b32_e32 v48, 1, v34
	v_lshl_or_b32 v49, v34, 2, v0
	s_mov_b32 s10, s94
	v_and_b32_e32 v19, 63, v222
	v_readfirstlane_b32 s81, v222
	s_nop 3
	s_lshr_b32 s81, s81, 6
	s_mov_b32 s80, 0

; DI int otid() { int t = __builtin_amdgcn_workitem_id_x(); asm volatile("" : "+v"(t)); return t; }
; DI int perm23(int i) { return (i & 0x13) | (((i >> 3) & 1) << 2) | (((i >> 2) & 1) << 3); }
; DI void attn_item(const Params& p, char* lds, int item) {
;   char* ws = p.ws;
;   const int tid = otid(), lane = tid & 63, wave = tid >> 6, l31 = lane & 31, hh = lane >> 5;
;   const int b = item >> 8, h = (item >> 5) & 7, c0 = (item & 31) * 4;
;   const int qc = c0 + (wave >> 1), qt = wave & 1;
;   const u16* PA = (const u16*)(ws + OFF_PA); const u16* VTa = (const u16*)(ws + OFF_VTA); u16* MIX = (u16*)(ws + OFF_MIX);
;   u16* Kl = (u16*)lds;
;   u16* Vl = Kl + 2 * 64 * 72;
;   float* biasl = (float*)(Vl + 2 * 64 * 72);
;   const int pi = perm23(l31);
;   const int sr = tid >> 3, sc8 = (tid & 7) * 8;
;   const u16* kg = PA + ((size_t)b * SEQ + sr) * 1024 + 512 + h * 64 + sc8;
;   const u16* vg = VTa + ((size_t)((b * 8 + h) * 64 + sr)) * SEQ + sc8;
;   for (int i = tid; i < 257; i += 512) biasl[i] = p.in[10][h * 257 + i] * 1.4426950408889634f;
;   const size_t q0 = (size_t)b * SEQ + qc * 64 + qt * 32;
; DI void phase_mixA(const Params& p, char* lds) {
;     ...
;   if ((gridDim.x & 7) == 0 && gridDim.x <= 256) {
;     const int x = blockIdx.x & 7, slot = blockIdx.x >> 3, nx = gridDim.x >> 3;
;     for (int j = slot; j < 256; j += nx) attn_item(p, lds, x * 256 + j);
;   } else {
;     for (int it = blockIdx.x; it < 2048; it += gridDim.x) attn_item(p, lds, it);
;   }
.LBB0_342:
	s_waitcnt vmcnt(0)
	s_cmp_eq_u32 s98, 2
	s_cbranch_scc1 .LBB0_410
	v_readlane_b32 s4, v250, 0
	v_readlane_b32 s5, v250, 1
	s_load_dword s0, s[4:5], 0x10
	s_load_dword s2, s[4:5], 0x0
	s_waitcnt lgkmcnt(0)
	s_lshr_b32 s0, s0, 16
	s_cmp_lg_u32 s0, 0
	s_cselect_b64 s[0:1], -1, 0
	s_cmp_lg_u64 s[0:1], 0
	s_addc_u32 s2, s2, 0
	s_and_b32 s0, s2, 7
	s_cmp_eq_u32 s0, 0
	s_cselect_b64 s[0:1], -1, 0
	s_cmpk_lt_u32 s2, 0x101
	s_cselect_b64 s[4:5], -1, 0
	s_and_b64 s[4:5], s[4:5], s[0:1]
	s_mov_b64 s[0:1], -1
	s_and_b64 vcc, exec, s[4:5]
	s_cbranch_vccnz .LBB0_376
	s_cmpk_gt_i32 s94, 0x7ff
	s_cbranch_scc1 .LBB0_375
	s_add_u32 s4, s68, 0x2a800000
	s_addc_u32 s5, s69, 0
	s_add_u32 s6, s68, 0x1e800000
	s_addc_u32 s7, s69, 0
	s_lshl_b32 s13, s94, 2
	s_lshl_b32 s15, s2, 2
	s_movk_i32 s8, 0x800
	s_mov_b32 s11, 0
	s_add_i32 s34, 0, 0x9000
	s_mov_b32 s12, 0x3fb8aa3b
	v_mov_b32_e32 v1, 0
	s_movk_i32 s35, 0x90
	s_movk_i32 s42, 0xff61
	s_movk_i32 s43, 0xff80
	s_mov_b32 s14, 0x3e38aa3b
	s_movk_i32 s48, 0xff7f
	s_mov_b32 s49, 0xff800000
	s_movk_i32 s50, 0xff7e
	s_movk_i32 s51, 0xff7d
	s_movk_i32 s54, 0xff7c
	s_movk_i32 s55, 0xff7b
	s_movk_i32 s56, 0xff7a
	s_movk_i32 s57, 0xff79
	s_movk_i32 s58, 0xff70
	s_movk_i32 s59, 0xff6f
	s_movk_i32 s60, 0xff6e
	s_movk_i32 s61, 0xff6d
	s_movk_i32 s72, 0xff6c
	s_movk_i32 s73, 0xff6b
	s_movk_i32 s74, 0xff6a
	s_movk_i32 s75, 0xff69
	v_mbcnt_hi_u32_b32 v114, -1, v203
	v_mov_b32_e32 v115, 0x80
	v_mov_b32_e32 v116, 0x7f
	v_mov_b32_e32 v117, 0x7e
	v_mov_b32_e32 v118, 0x7d
	v_mov_b32_e32 v119, 0x7c
	v_mov_b32_e32 v120, 0x7b
	v_mov_b32_e32 v121, 0x7a
	v_mov_b32_e32 v122, 0x79
	v_mov_b32_e32 v123, 0x70
	v_mov_b32_e32 v124, 0x6f
	v_mov_b32_e32 v125, 0x6e
	v_mov_b32_e32 v126, 0x6d
	v_mov_b32_e32 v127, 0x6c
	v_mov_b32_e32 v128, 0x6b
	v_mov_b32_e32 v129, 0x6a
	v_mov_b32_e32 v130, 0x69
	s_mov_b32 s76, s94
	s_branch .LBB0_346

; DI void phase_mixA(const Params& p, char* lds) {
;     ...
;   if ((gridDim.x & 7) == 0 && gridDim.x <= 256) {
;     const int x = blockIdx.x & 7, slot = blockIdx.x >> 3, nx = gridDim.x >> 3;
;     for (int j = slot; j < 256; j += nx) attn_item(p, lds, x * 256 + j);
;   } else {
;     for (int it = blockIdx.x; it < 2048; it += gridDim.x) attn_item(p, lds, it);
;   }
.Lmixa_bexit:
	s_cmp_eq_u32 s98, 1
	s_cbranch_scc0 .LBB0_410
	s_mov_b32 s98, 2
	s_waitcnt vmcnt(0) lgkmcnt(0)
	s_barrier
	s_branch .Lmixa_astart
